# loadprio + packed SwiGLU epilogue + B fragment reads off one base VGPR with immediate offsets (4 fewer VALU per loop iteration)
# speedup vs baseline: 1.0062x; 1.0062x over previous
; #define PG8_STAGE(bufoff, gbase, voff) do { _Pragma("unroll") for (int _i = 0; _i < 2; ++_i) \
;         __builtin_amdgcn_global_load_lds((const unsigned*)((const char*)(gbase) + (voff)[_i]), (PG8_LAS unsigned*)(lds + (bufoff) + ldsw + _i * 8192), 16, 0, 0); } while (0)
; #define PG8_WAIT_V(n) asm volatile("s_waitcnt vmcnt(" #n ")" ::: "memory")
; #define PG8_BAR __builtin_amdgcn_s_barrier()
; template <class Epi, class Sched, bool ALIGN_EPI = false, bool SP2 = false>
; __device__ __forceinline__ void gemm_phase(PG8_LAS unsigned char* lds, const Gemm g, const Sched& S, const Epi& E, int tid_in) {
;     ...
;     const unsigned ldsw = (unsigned)wid * 1024u;
;     const int aoff = lds_byte(wr * 64 + fr, fq * 8), boff = lds_byte(wc * 32 + fr, fq * 8);
;     ...
;     Unit cur, nxt; int ui = 0;
;     if (!S.next(0, cur)) return;
;     f32x4 acc[2][2][4][2];
; #pragma unroll
;     for (int a = 0; a < 2; ++a)
; #pragma unroll
;         for (int b = 0; b < 2; ++b)
; #pragma unroll
;             for (int m = 0; m < 4; ++m)
; #pragma unroll
;                 for (int n = 0; n < 2; ++n) acc[a][b][m][n] = (f32x4){0.f, 0.f, 0.f, 0.f};
;     bf16x8 At[4][2], B0[2][2], B1[2][2];
;     const char* cA = (const char*)g.A + (size_t)cur.pm * tstep; const char* cB = (const char*)g.Bt + (size_t)cur.pn * tstep;
;     S.a_ready(cur);
;     if constexpr (SP2) {
;         PG8_STAGE(PG8_SB(0, 0), cB, voffB); PG8_STAGE(PG8_SB(0, 1), cB + hstep, voffB); PG8_STAGE(PG8_SA(0, 0), cA, voffA); PG8_STAGE(PG8_SA(0, 1), cA + hstep, voffA);
;         if (wr == 1) PG8_BAR;
;         PG8_WAIT_V(2); PG8_BAR;
;         PG8_STAGE(PG8_SB(1, 0), cB + kstep, voffB); PG8_STAGE(PG8_SA(1, 0), cA + kstep, voffA); PG8_STAGE(PG8_SB(1, 1), cB + hstep + kstep, voffB);
;         PG8_WAIT_V(6); PG8_BAR;
.LBB0_582:
	v_lshl_add_u64 v[150:151], v[4:5], 0, s[40:41]
	v_lshrrev_b32_e32 v5, 1, v20
	v_and_b32_e32 v21, 24, v5
	v_and_b32_e32 v4, 15, v20
	v_lshlrev_b32_e32 v5, 1, v21
	v_lshl_or_b32 v163, s2, 6, v4
	v_lshl_or_b32 v4, v4, 6, v5
	v_lshlrev_b32_e32 v5, 2, v20
	s_lshl_b32 s2, s2, 13
	v_and_b32_e32 v5, 32, v5
	s_lshl_b32 s1, s1, 5
	v_bitop3_b32 v20, v4, s2, v5 bitop3:0xde
	s_and_b32 s2, s1, 0x60
	s_lshl_b32 s1, s2, 7
	v_bitop3_b32 v168, v4, s1, v5 bitop3:0xde
	v_add_u32_e32 v173, 0x10000, v168
	s_add_i32 m0, s15, 0x18000
	v_lshl_add_u64 v[4:5], v[6:7], 0, s[70:71]
	s_waitcnt vmcnt(2)
	s_barrier
	global_load_lds_dwordx4 v[4:5], off
	v_lshl_add_u64 v[4:5], v[8:9], 0, s[70:71]
	s_add_i32 m0, s15, 0x1a000
	s_add_i32 s19, s15, 0x8000
	global_load_lds_dwordx4 v[4:5], off
	v_lshl_add_u64 v[4:5], v[10:11], 0, s[70:71]
	s_mov_b32 m0, s19
	s_add_i32 s1, s15, 0xa000
	global_load_lds_dwordx4 v[4:5], off
	v_lshl_add_u64 v[4:5], v[12:13], 0, s[70:71]
	s_mov_b32 m0, s1
	v_or_b32_e32 v169, s2, v21
	global_load_lds_dwordx4 v[4:5], off
	v_lshl_add_u64 v[4:5], v[0:1], 0, s[86:87]
	s_add_i32 m0, s15, 0x1c000
	v_lshl_add_u64 v[6:7], v[4:5], 0, v[128:129]
	global_load_lds_dwordx4 v[6:7], off
	v_lshl_add_u64 v[4:5], v[4:5], 0, v[144:145]
	s_add_i32 m0, s15, 0x1e000
	s_cmpk_lt_u32 s0, 0x100
	global_load_lds_dwordx4 v[4:5], off
	v_lshlrev_b32_e32 v4, 15, v14
	v_and_b32_e32 v4, 0xffff0000, v4
	v_lshl_add_u32 v4, v15, 12, v4
	v_and_b32_e32 v5, 1, v14
	v_lshl_or_b32 v4, v5, 6, v4
	v_lshl_add_u32 v152, v16, 1, v4
	v_lshlrev_b32_e32 v4, 15, v18
	v_and_b32_e32 v4, 0xffff0000, v4
	s_waitcnt vmcnt(6)
	v_lshl_add_u32 v4, v17, 12, v4
	v_and_b32_e32 v5, 1, v18
	v_lshl_or_b32 v4, v5, 6, v4
	v_readlane_b32 s2, v254, 38
	s_cselect_b64 s[8:9], -1, 0
	v_mov_b32_e32 v153, v129
	v_lshl_add_u32 v154, v19, 1, v4
	v_mov_b32_e32 v155, v129
	s_mov_b32 s0, 0
	v_add_u32_e32 v175, 0, v20
	v_readlane_b32 s20, v254, 37
	s_mov_b32 s21, s2
	s_barrier
	v_readlane_b32 s3, v254, 39
	s_branch .LBB0_585

; #define PG8_STAGE(bufoff, gbase, voff) do { _Pragma("unroll") for (int _i = 0; _i < 2; ++_i) \
;         __builtin_amdgcn_global_load_lds((const unsigned*)((const char*)(gbase) + (voff)[_i]), (PG8_LAS unsigned*)(lds + (bufoff) + ldsw + _i * 8192), 16, 0, 0); } while (0)
; #define PG8_LDA(dst, b, h) do { _Pragma("unroll") for (int m = 0; m < 4; ++m) _Pragma("unroll") for (int k = 0; k < 2; ++k) dst[m][k] = *(const PG8_LAS bf16x8*)(lds + PG8_SA(b, h) + aoff + m * 2048 + k * 1024); } while (0)
; #define PG8_LDB(dst, b, h) do { _Pragma("unroll") for (int n = 0; n < 2; ++n) _Pragma("unroll") for (int k = 0; k < 2; ++k) dst[n][k] = *(const PG8_LAS bf16x8*)(lds + PG8_SB(b, h) + boff + n * 2048 + k * 1024); } while (0)
; #define PG8_MMA(ai, bj, At, Bt) do { __builtin_amdgcn_s_setprio(1); _Pragma("unroll") for (int m = 0; m < 4; ++m) _Pragma("unroll") for (int n = 0; n < 2; ++n) _Pragma("unroll") for (int k = 0; k < 2; ++k) \
;         acc[ai][bj][m][n] = __builtin_amdgcn_mfma_f32_16x16x32_bf16(Bt[n][k], At[m][k], acc[ai][bj][m][n], 0, 0, 0); __builtin_amdgcn_s_setprio(0); } while (0)
; #define PG8_WAIT_V(n) asm volatile("s_waitcnt vmcnt(" #n ")" ::: "memory")
; #define PG8_WAIT_L(n) asm volatile("s_waitcnt lgkmcnt(" #n ")" ::: "memory")
; #define PG8_BAR __builtin_amdgcn_s_barrier()
; #define PG8_SCHED __builtin_amdgcn_sched_barrier(0)
; template <class Epi, class Sched, bool ALIGN_EPI = false, bool SP2 = false>
; __device__ __forceinline__ void gemm_phase(PG8_LAS unsigned char* lds, const Gemm g, const Sched& S, const Epi& E, int tid_in) {
;     ...
;             PG8_LDB(B0, 0, 0); PG8_LDB(B1, 0, 1); PG8_SCHED; PG8_LDA(At, 0, 0); PG8_STAGE(PG8_SA(1, 1), a1 + hstep, voffA);
;             PG8_WAIT_V(8); PG8_WAIT_L(0); PG8_BAR; PG8_MMA(0, 0, At, B0); PG8_MMA(0, 1, At, B1); PG8_BAR; PG8_SCHED;
;             PG8_LDA(At, 0, 1); PG8_STAGE(PG8_SB(0, 0), b2, voffB); PG8_STAGE(PG8_SB(0, 1), b2 + hstep, voffB); PG8_STAGE(PG8_SA(0, 0), a2, voffA);
;             PG8_WAIT_V(8); PG8_WAIT_L(0); PG8_BAR; PG8_MMA(1, 0, At, B0); PG8_MMA(1, 1, At, B1); PG8_BAR; PG8_SCHED;
.LBB0_588:
	s_cmp_eq_u32 s2, 28
	s_cselect_b64 vcc, -1, 0
	s_add_i32 s3, 0, 0x10000
	s_add_i32 s11, 0, 0x14000
	v_lshl_add_u64 v[176:177], v[166:167], 0, s[52:53]
	v_cndmask_b32_e32 v241, v177, v131, vcc
	v_cndmask_b32_e32 v240, v176, v160, vcc
	ds_read_b128 v[176:179], v173
	ds_read_b128 v[180:183], v173 offset:1024
	ds_read_b128 v[184:187], v173 offset:2048
	ds_read_b128 v[188:191], v173 offset:3072
	ds_read_b128 v[192:195], v173 offset:16384
	ds_read_b128 v[196:199], v173 offset:17408
	ds_read_b128 v[200:203], v173 offset:18432
	ds_read_b128 v[204:207], v173 offset:19456
	v_cndmask_b32_e32 v243, v165, v161, vcc
	v_cndmask_b32_e32 v242, v164, v162, vcc
	v_lshl_add_u64 v[244:245], v[166:167], 0, v[154:155]
	s_add_i32 m0, s15, 0xc000
	ds_read_b128 v[208:211], v175
	ds_read_b128 v[212:215], v175 offset:1024
	ds_read_b128 v[216:219], v175 offset:2048
	ds_read_b128 v[220:223], v175 offset:3072
	ds_read_b128 v[224:227], v175 offset:4096
	ds_read_b128 v[228:231], v175 offset:5120
	ds_read_b128 v[232:235], v175 offset:6144
	ds_read_b128 v[236:239], v175 offset:7168
	global_load_lds_dwordx4 v[244:245], off
	v_lshl_add_u64 v[244:245], v[166:167], 0, v[152:153]
	s_add_i32 m0, s15, 0xe000
	s_nop 0
	global_load_lds_dwordx4 v[244:245], off
	s_setprio 0
	s_waitcnt vmcnt(8) lgkmcnt(0)
	s_barrier
	v_mfma_f32_16x16x32_bf16 v[124:127], v[176:179], v[208:211], v[124:127]
	v_mfma_f32_16x16x32_bf16 v[116:119], v[184:187], v[208:211], v[116:119]
	v_mfma_f32_16x16x32_bf16 v[108:111], v[176:179], v[216:219], v[108:111]
	v_mfma_f32_16x16x32_bf16 v[100:103], v[184:187], v[216:219], v[100:103]
	v_mfma_f32_16x16x32_bf16 v[92:95], v[176:179], v[224:227], v[92:95]
	v_mfma_f32_16x16x32_bf16 v[84:87], v[184:187], v[224:227], v[84:87]
	v_mfma_f32_16x16x32_bf16 v[76:79], v[176:179], v[232:235], v[76:79]
	v_mfma_f32_16x16x32_bf16 v[68:71], v[184:187], v[232:235], v[68:71]
	v_mfma_f32_16x16x32_bf16 v[124:127], v[180:183], v[212:215], v[124:127]
	v_mfma_f32_16x16x32_bf16 v[116:119], v[188:191], v[212:215], v[116:119]
	v_mfma_f32_16x16x32_bf16 v[108:111], v[180:183], v[220:223], v[108:111]
	v_mfma_f32_16x16x32_bf16 v[100:103], v[188:191], v[220:223], v[100:103]
	v_mfma_f32_16x16x32_bf16 v[92:95], v[180:183], v[228:231], v[92:95]
	v_mfma_f32_16x16x32_bf16 v[84:87], v[188:191], v[228:231], v[84:87]
	v_mfma_f32_16x16x32_bf16 v[76:79], v[180:183], v[236:239], v[76:79]
	v_mfma_f32_16x16x32_bf16 v[68:71], v[188:191], v[236:239], v[68:71]
	v_mfma_f32_16x16x32_bf16 v[120:123], v[192:195], v[208:211], v[120:123]
	v_mfma_f32_16x16x32_bf16 v[112:115], v[200:203], v[208:211], v[112:115]
	v_mfma_f32_16x16x32_bf16 v[104:107], v[192:195], v[216:219], v[104:107]
	v_mfma_f32_16x16x32_bf16 v[96:99], v[200:203], v[216:219], v[96:99]
	v_mfma_f32_16x16x32_bf16 v[88:91], v[192:195], v[224:227], v[88:91]
	v_mfma_f32_16x16x32_bf16 v[80:83], v[200:203], v[224:227], v[80:83]
	v_mfma_f32_16x16x32_bf16 v[72:75], v[192:195], v[232:235], v[72:75]
	v_mfma_f32_16x16x32_bf16 v[64:67], v[200:203], v[232:235], v[64:67]
	v_mfma_f32_16x16x32_bf16 v[120:123], v[196:199], v[212:215], v[120:123]
	v_mfma_f32_16x16x32_bf16 v[112:115], v[204:207], v[212:215], v[112:115]
	v_mfma_f32_16x16x32_bf16 v[104:107], v[196:199], v[220:223], v[104:107]
	v_mfma_f32_16x16x32_bf16 v[96:99], v[204:207], v[220:223], v[96:99]
	v_mfma_f32_16x16x32_bf16 v[88:91], v[196:199], v[228:231], v[88:91]
	v_mfma_f32_16x16x32_bf16 v[80:83], v[204:207], v[228:231], v[80:83]
	v_mfma_f32_16x16x32_bf16 v[72:75], v[196:199], v[236:239], v[72:75]
	v_mfma_f32_16x16x32_bf16 v[64:67], v[204:207], v[236:239], v[64:67]
	s_barrier
	s_setprio 1
	s_add_i32 s3, s3, s14
	v_lshl_add_u64 v[244:245], v[242:243], 0, v[128:129]
	s_mov_b32 m0, s3
	ds_read_b128 v[208:211], v175 offset:16384
	ds_read_b128 v[212:215], v175 offset:17408
	ds_read_b128 v[216:219], v175 offset:18432
	ds_read_b128 v[220:223], v175 offset:19456
	ds_read_b128 v[224:227], v175 offset:20480
	ds_read_b128 v[228:231], v175 offset:21504
	ds_read_b128 v[232:235], v175 offset:22528
	ds_read_b128 v[236:239], v175 offset:23552
	global_load_lds_dwordx4 v[244:245], off
	v_lshl_add_u64 v[246:247], v[242:243], 0, v[144:145]
	s_add_i32 m0, s3, 0x2000
	v_lshl_add_u64 v[248:249], v[242:243], 0, s[98:99]
	s_add_i32 s3, s11, s14
	global_load_lds_dwordx4 v[246:247], off
	v_lshl_add_u64 v[250:251], v[248:249], 0, v[128:129]
	s_mov_b32 m0, s3
	v_lshl_add_u64 v[248:249], v[248:249], 0, v[144:145]
	global_load_lds_dwordx4 v[250:251], off
	s_add_i32 m0, s3, 0x2000
	v_lshl_add_u64 v[250:251], v[240:241], 0, v[146:147]
	global_load_lds_dwordx4 v[248:249], off
	v_lshl_add_u64 v[248:249], v[240:241], 0, v[148:149]
	s_mov_b32 m0, s15
	s_nop 0
	global_load_lds_dwordx4 v[248:249], off
	s_mov_b32 m0, s16
	s_nop 0
	global_load_lds_dwordx4 v[250:251], off
	s_setprio 0
	s_waitcnt vmcnt(8) lgkmcnt(0)
	s_barrier
; #define PG8_STAGE(bufoff, gbase, voff) do { _Pragma("unroll") for (int _i = 0; _i < 2; ++_i) \
;         __builtin_amdgcn_global_load_lds((const unsigned*)((const char*)(gbase) + (voff)[_i]), (PG8_LAS unsigned*)(lds + (bufoff) + ldsw + _i * 8192), 16, 0, 0); } while (0)
; #define PG8_LDA(dst, b, h) do { _Pragma("unroll") for (int m = 0; m < 4; ++m) _Pragma("unroll") for (int k = 0; k < 2; ++k) dst[m][k] = *(const PG8_LAS bf16x8*)(lds + PG8_SA(b, h) + aoff + m * 2048 + k * 1024); } while (0)
; #define PG8_LDB(dst, b, h) do { _Pragma("unroll") for (int n = 0; n < 2; ++n) _Pragma("unroll") for (int k = 0; k < 2; ++k) dst[n][k] = *(const PG8_LAS bf16x8*)(lds + PG8_SB(b, h) + boff + n * 2048 + k * 1024); } while (0)
; #define PG8_MMA(ai, bj, At, Bt) do { __builtin_amdgcn_s_setprio(1); _Pragma("unroll") for (int m = 0; m < 4; ++m) _Pragma("unroll") for (int n = 0; n < 2; ++n) _Pragma("unroll") for (int k = 0; k < 2; ++k) \
;         acc[ai][bj][m][n] = __builtin_amdgcn_mfma_f32_16x16x32_bf16(Bt[n][k], At[m][k], acc[ai][bj][m][n], 0, 0, 0); __builtin_amdgcn_s_setprio(0); } while (0)
; #define PG8_WAIT_V(n) asm volatile("s_waitcnt vmcnt(" #n ")" ::: "memory")
; #define PG8_WAIT_L(n) asm volatile("s_waitcnt lgkmcnt(" #n ")" ::: "memory")
; #define PG8_BAR __builtin_amdgcn_s_barrier()
; #define PG8_SCHED __builtin_amdgcn_sched_barrier(0)
; template <class Epi, class Sched, bool ALIGN_EPI = false, bool SP2 = false>
; __device__ __forceinline__ void gemm_phase(PG8_LAS unsigned char* lds, const Gemm g, const Sched& S, const Epi& E, int tid_in) {
;     ...
;             PG8_WAIT_V(8); PG8_WAIT_L(0); PG8_BAR; PG8_MMA(1, 0, At, B0); PG8_MMA(1, 1, At, B1); PG8_BAR; PG8_SCHED;
;             PG8_LDB(B0, 1, 0); PG8_LDB(B1, 1, 1); PG8_SCHED; PG8_LDA(At, 1, 0); PG8_STAGE(PG8_SA(0, 1), a2 + hstep, voffA);
;             PG8_WAIT_V(8); PG8_WAIT_L(0); PG8_BAR; PG8_MMA(0, 0, At, B0); PG8_MMA(0, 1, At, B1); PG8_BAR; PG8_SCHED;
	v_mfma_f32_16x16x32_bf16 v[60:63], v[176:179], v[208:211], v[60:63]
	v_mfma_f32_16x16x32_bf16 v[52:55], v[184:187], v[208:211], v[52:55]
	v_mfma_f32_16x16x32_bf16 v[44:47], v[176:179], v[216:219], v[44:47]
	v_mfma_f32_16x16x32_bf16 v[36:39], v[184:187], v[216:219], v[36:39]
	v_mfma_f32_16x16x32_bf16 v[28:31], v[176:179], v[224:227], v[28:31]
	v_mfma_f32_16x16x32_bf16 v[20:23], v[184:187], v[224:227], v[20:23]
	v_mfma_f32_16x16x32_bf16 v[12:15], v[176:179], v[232:235], v[12:15]
	v_mfma_f32_16x16x32_bf16 v[4:7], v[184:187], v[232:235], v[4:7]
	v_mfma_f32_16x16x32_bf16 v[60:63], v[180:183], v[212:215], v[60:63]
	v_mfma_f32_16x16x32_bf16 v[52:55], v[188:191], v[212:215], v[52:55]
	v_mfma_f32_16x16x32_bf16 v[44:47], v[180:183], v[220:223], v[44:47]
	v_mfma_f32_16x16x32_bf16 v[36:39], v[188:191], v[220:223], v[36:39]
	v_mfma_f32_16x16x32_bf16 v[28:31], v[180:183], v[228:231], v[28:31]
	v_mfma_f32_16x16x32_bf16 v[20:23], v[188:191], v[228:231], v[20:23]
	v_mfma_f32_16x16x32_bf16 v[12:15], v[180:183], v[236:239], v[12:15]
	v_mfma_f32_16x16x32_bf16 v[4:7], v[188:191], v[236:239], v[4:7]
	v_mfma_f32_16x16x32_bf16 v[56:59], v[192:195], v[208:211], v[56:59]
	v_mfma_f32_16x16x32_bf16 v[48:51], v[200:203], v[208:211], v[48:51]
	v_mfma_f32_16x16x32_bf16 v[40:43], v[192:195], v[216:219], v[40:43]
	v_mfma_f32_16x16x32_bf16 v[32:35], v[200:203], v[216:219], v[32:35]
	v_mfma_f32_16x16x32_bf16 v[24:27], v[192:195], v[224:227], v[24:27]
	v_mfma_f32_16x16x32_bf16 v[16:19], v[200:203], v[224:227], v[16:19]
	v_mfma_f32_16x16x32_bf16 v[8:11], v[192:195], v[232:235], v[8:11]
	v_mfma_f32_16x16x32_bf16 v[0:3], v[200:203], v[232:235], v[0:3]
	v_mfma_f32_16x16x32_bf16 v[56:59], v[196:199], v[212:215], v[56:59]
	v_mfma_f32_16x16x32_bf16 v[48:51], v[204:207], v[212:215], v[48:51]
	v_mfma_f32_16x16x32_bf16 v[40:43], v[196:199], v[220:223], v[40:43]
	v_mfma_f32_16x16x32_bf16 v[32:35], v[204:207], v[220:223], v[32:35]
	v_mfma_f32_16x16x32_bf16 v[24:27], v[196:199], v[228:231], v[24:27]
	v_mfma_f32_16x16x32_bf16 v[16:19], v[204:207], v[228:231], v[16:19]
	v_mfma_f32_16x16x32_bf16 v[8:11], v[196:199], v[236:239], v[8:11]
	v_mfma_f32_16x16x32_bf16 v[0:3], v[204:207], v[236:239], v[0:3]
	s_barrier
	s_setprio 1
	s_add_i32 s3, 0, 0x18000
	s_add_i32 s11, 0, 0x1c000
	ds_read_b128 v[176:179], v173 offset:32768
	ds_read_b128 v[180:183], v173 offset:33792
	ds_read_b128 v[184:187], v173 offset:34816
	ds_read_b128 v[188:191], v173 offset:35840
	ds_read_b128 v[192:195], v173 offset:49152
	ds_read_b128 v[196:199], v173 offset:50176
	ds_read_b128 v[200:203], v173 offset:51200
	ds_read_b128 v[204:207], v173 offset:52224
	v_lshl_add_u64 v[240:241], v[240:241], 0, s[98:99]
	s_mov_b32 m0, s17
	v_lshl_add_u64 v[252:253], v[240:241], 0, v[148:149]
	ds_read_b128 v[208:211], v175 offset:32768
	ds_read_b128 v[212:215], v175 offset:33792
	ds_read_b128 v[216:219], v175 offset:34816
	ds_read_b128 v[220:223], v175 offset:35840
	ds_read_b128 v[224:227], v175 offset:36864
	ds_read_b128 v[228:231], v175 offset:37888
	ds_read_b128 v[232:235], v175 offset:38912
	ds_read_b128 v[236:239], v175 offset:39936
	global_load_lds_dwordx4 v[252:253], off
	v_lshl_add_u64 v[240:241], v[240:241], 0, v[146:147]
	s_mov_b32 m0, s18
	s_nop 0
	global_load_lds_dwordx4 v[240:241], off
	s_setprio 0
	s_waitcnt vmcnt(8) lgkmcnt(0)
	s_barrier
	v_mfma_f32_16x16x32_bf16 v[124:127], v[176:179], v[208:211], v[124:127]
	v_mfma_f32_16x16x32_bf16 v[116:119], v[184:187], v[208:211], v[116:119]
	v_mfma_f32_16x16x32_bf16 v[108:111], v[176:179], v[216:219], v[108:111]
	v_mfma_f32_16x16x32_bf16 v[100:103], v[184:187], v[216:219], v[100:103]
	v_mfma_f32_16x16x32_bf16 v[92:95], v[176:179], v[224:227], v[92:95]
	v_mfma_f32_16x16x32_bf16 v[84:87], v[184:187], v[224:227], v[84:87]
	v_mfma_f32_16x16x32_bf16 v[76:79], v[176:179], v[232:235], v[76:79]
	v_mfma_f32_16x16x32_bf16 v[68:71], v[184:187], v[232:235], v[68:71]
	v_mfma_f32_16x16x32_bf16 v[124:127], v[180:183], v[212:215], v[124:127]
	v_mfma_f32_16x16x32_bf16 v[116:119], v[188:191], v[212:215], v[116:119]
	v_mfma_f32_16x16x32_bf16 v[108:111], v[180:183], v[220:223], v[108:111]
	v_mfma_f32_16x16x32_bf16 v[100:103], v[188:191], v[220:223], v[100:103]
	v_mfma_f32_16x16x32_bf16 v[92:95], v[180:183], v[228:231], v[92:95]
	v_mfma_f32_16x16x32_bf16 v[84:87], v[188:191], v[228:231], v[84:87]
	v_mfma_f32_16x16x32_bf16 v[76:79], v[180:183], v[236:239], v[76:79]
	v_mfma_f32_16x16x32_bf16 v[68:71], v[188:191], v[236:239], v[68:71]
	v_mfma_f32_16x16x32_bf16 v[120:123], v[192:195], v[208:211], v[120:123]
	v_mfma_f32_16x16x32_bf16 v[112:115], v[200:203], v[208:211], v[112:115]
	v_mfma_f32_16x16x32_bf16 v[104:107], v[192:195], v[216:219], v[104:107]
	v_mfma_f32_16x16x32_bf16 v[96:99], v[200:203], v[216:219], v[96:99]
	v_mfma_f32_16x16x32_bf16 v[88:91], v[192:195], v[224:227], v[88:91]
	v_mfma_f32_16x16x32_bf16 v[80:83], v[200:203], v[224:227], v[80:83]
	v_mfma_f32_16x16x32_bf16 v[72:75], v[192:195], v[232:235], v[72:75]
	v_mfma_f32_16x16x32_bf16 v[64:67], v[200:203], v[232:235], v[64:67]
	v_mfma_f32_16x16x32_bf16 v[120:123], v[196:199], v[212:215], v[120:123]
	v_mfma_f32_16x16x32_bf16 v[112:115], v[204:207], v[212:215], v[112:115]
	v_mfma_f32_16x16x32_bf16 v[104:107], v[196:199], v[220:223], v[104:107]
	v_mfma_f32_16x16x32_bf16 v[96:99], v[204:207], v[220:223], v[96:99]
	v_mfma_f32_16x16x32_bf16 v[88:91], v[196:199], v[228:231], v[88:91]
	v_mfma_f32_16x16x32_bf16 v[80:83], v[204:207], v[228:231], v[80:83]
	v_mfma_f32_16x16x32_bf16 v[72:75], v[196:199], v[236:239], v[72:75]
	v_mfma_f32_16x16x32_bf16 v[64:67], v[204:207], v[236:239], v[64:67]
	s_barrier
; #define PG8_STAGE(bufoff, gbase, voff) do { _Pragma("unroll") for (int _i = 0; _i < 2; ++_i) \
;         __builtin_amdgcn_global_load_lds((const unsigned*)((const char*)(gbase) + (voff)[_i]), (PG8_LAS unsigned*)(lds + (bufoff) + ldsw + _i * 8192), 16, 0, 0); } while (0)
; #define PG8_LDA(dst, b, h) do { _Pragma("unroll") for (int m = 0; m < 4; ++m) _Pragma("unroll") for (int k = 0; k < 2; ++k) dst[m][k] = *(const PG8_LAS bf16x8*)(lds + PG8_SA(b, h) + aoff + m * 2048 + k * 1024); } while (0)
; #define PG8_MMA(ai, bj, At, Bt) do { __builtin_amdgcn_s_setprio(1); _Pragma("unroll") for (int m = 0; m < 4; ++m) _Pragma("unroll") for (int n = 0; n < 2; ++n) _Pragma("unroll") for (int k = 0; k < 2; ++k) \
;         acc[ai][bj][m][n] = __builtin_amdgcn_mfma_f32_16x16x32_bf16(Bt[n][k], At[m][k], acc[ai][bj][m][n], 0, 0, 0); __builtin_amdgcn_s_setprio(0); } while (0)
; #define PG8_WAIT_V(n) asm volatile("s_waitcnt vmcnt(" #n ")" ::: "memory")
; #define PG8_WAIT_L(n) asm volatile("s_waitcnt lgkmcnt(" #n ")" ::: "memory")
; #define PG8_BAR __builtin_amdgcn_s_barrier()
; #define PG8_SCHED __builtin_amdgcn_sched_barrier(0)
; template <class Epi, class Sched, bool ALIGN_EPI = false, bool SP2 = false>
; __device__ __forceinline__ void gemm_phase(PG8_LAS unsigned char* lds, const Gemm g, const Sched& S, const Epi& E, int tid_in) {
;     ...
;         for (int t = 0; t < nt; t += 2) {
;             const bool last = (t == nt - 2);
;             const char* a1 = cA + (size_t)(t + 1) * kstep;
;             const char* a2 = last ? nA : cA + (size_t)(t + 2) * kstep; const char* b2 = last ? nB : cB + (size_t)(t + 2) * kstep;
;             const char* a3 = a2 + kstep; const char* b3 = b2 + kstep;
;     ...
;             PG8_LDA(At, 1, 1); PG8_STAGE(PG8_SB(1, 0), b3, voffB); PG8_STAGE(PG8_SB(1, 1), b3 + hstep, voffB); PG8_STAGE(PG8_SA(1, 0), a3, voffA);
;             PG8_WAIT_V(8); PG8_WAIT_L(0); PG8_BAR; PG8_MMA(1, 0, At, B0); PG8_MMA(1, 1, At, B1); PG8_BAR; PG8_SCHED;
	s_setprio 1
	s_add_i32 s3, s3, s14
	v_lshl_add_u64 v[240:241], v[244:245], 0, s[70:71]
	s_mov_b32 m0, s3
	ds_read_b128 v[208:211], v175 offset:49152
	ds_read_b128 v[212:215], v175 offset:50176
	ds_read_b128 v[216:219], v175 offset:51200
	ds_read_b128 v[220:223], v175 offset:52224
	ds_read_b128 v[224:227], v175 offset:53248
	ds_read_b128 v[228:231], v175 offset:54272
	ds_read_b128 v[232:235], v175 offset:55296
	ds_read_b128 v[236:239], v175 offset:56320
	global_load_lds_dwordx4 v[240:241], off
	v_lshl_add_u64 v[240:241], v[246:247], 0, s[70:71]
	s_add_i32 m0, s3, 0x2000
	s_add_i32 s3, s11, s14
	global_load_lds_dwordx4 v[240:241], off
	v_lshl_add_u64 v[240:241], v[242:243], 0, s[86:87]
	v_lshl_add_u64 v[242:243], v[240:241], 0, v[128:129]
	s_mov_b32 m0, s3
	v_lshl_add_u64 v[240:241], v[240:241], 0, v[144:145]
	global_load_lds_dwordx4 v[242:243], off
	s_add_i32 m0, s3, 0x2000
	s_nop 0
	global_load_lds_dwordx4 v[240:241], off
	v_lshl_add_u64 v[240:241], v[248:249], 0, s[70:71]
	s_mov_b32 m0, s19
	s_nop 0
	global_load_lds_dwordx4 v[240:241], off
	v_lshl_add_u64 v[240:241], v[250:251], 0, s[70:71]
	s_mov_b32 m0, s1
	s_nop 0
	global_load_lds_dwordx4 v[240:241], off
	s_setprio 0
	s_waitcnt vmcnt(8) lgkmcnt(0)
	s_barrier
	v_mfma_f32_16x16x32_bf16 v[60:63], v[176:179], v[208:211], v[60:63]
	v_mfma_f32_16x16x32_bf16 v[52:55], v[184:187], v[208:211], v[52:55]
	v_mfma_f32_16x16x32_bf16 v[44:47], v[176:179], v[216:219], v[44:47]
	v_mfma_f32_16x16x32_bf16 v[36:39], v[184:187], v[216:219], v[36:39]
	v_mfma_f32_16x16x32_bf16 v[28:31], v[176:179], v[224:227], v[28:31]
	v_mfma_f32_16x16x32_bf16 v[20:23], v[184:187], v[224:227], v[20:23]
	v_mfma_f32_16x16x32_bf16 v[12:15], v[176:179], v[232:235], v[12:15]
	v_mfma_f32_16x16x32_bf16 v[4:7], v[184:187], v[232:235], v[4:7]
	v_mfma_f32_16x16x32_bf16 v[60:63], v[180:183], v[212:215], v[60:63]
	v_mfma_f32_16x16x32_bf16 v[52:55], v[188:191], v[212:215], v[52:55]
	v_mfma_f32_16x16x32_bf16 v[44:47], v[180:183], v[220:223], v[44:47]
	v_mfma_f32_16x16x32_bf16 v[36:39], v[188:191], v[220:223], v[36:39]
	v_mfma_f32_16x16x32_bf16 v[28:31], v[180:183], v[228:231], v[28:31]
	v_mfma_f32_16x16x32_bf16 v[20:23], v[188:191], v[228:231], v[20:23]
	v_mfma_f32_16x16x32_bf16 v[12:15], v[180:183], v[236:239], v[12:15]
	v_mfma_f32_16x16x32_bf16 v[4:7], v[188:191], v[236:239], v[4:7]
	v_mfma_f32_16x16x32_bf16 v[56:59], v[192:195], v[208:211], v[56:59]
	v_mfma_f32_16x16x32_bf16 v[48:51], v[200:203], v[208:211], v[48:51]
	v_mfma_f32_16x16x32_bf16 v[40:43], v[192:195], v[216:219], v[40:43]
	v_mfma_f32_16x16x32_bf16 v[32:35], v[200:203], v[216:219], v[32:35]
	v_mfma_f32_16x16x32_bf16 v[24:27], v[192:195], v[224:227], v[24:27]
	v_mfma_f32_16x16x32_bf16 v[16:19], v[200:203], v[224:227], v[16:19]
	v_mfma_f32_16x16x32_bf16 v[8:11], v[192:195], v[232:235], v[8:11]
	v_mfma_f32_16x16x32_bf16 v[0:3], v[200:203], v[232:235], v[0:3]
	v_mfma_f32_16x16x32_bf16 v[56:59], v[196:199], v[212:215], v[56:59]
	v_mfma_f32_16x16x32_bf16 v[48:51], v[204:207], v[212:215], v[48:51]
	v_mfma_f32_16x16x32_bf16 v[40:43], v[196:199], v[220:223], v[40:43]
	v_mfma_f32_16x16x32_bf16 v[32:35], v[204:207], v[220:223], v[32:35]
	v_mfma_f32_16x16x32_bf16 v[24:27], v[196:199], v[228:231], v[24:27]
	v_mfma_f32_16x16x32_bf16 v[16:19], v[204:207], v[228:231], v[16:19]
	v_mfma_f32_16x16x32_bf16 v[8:11], v[196:199], v[236:239], v[8:11]
	v_mfma_f32_16x16x32_bf16 v[0:3], v[204:207], v[236:239], v[0:3]
	s_barrier
	s_setprio 1
	s_add_i32 s2, s2, 2
	v_lshl_add_u64 v[164:165], v[164:165], 0, s[82:83]
	s_cmp_gt_u32 s2, 29
	v_lshl_add_u64 v[166:167], v[166:167], 0, s[82:83]
	s_cbranch_scc0 .LBB0_588
	s_setprio 0
	s_and_b64 vcc, exec, s[8:9]
	s_cbranch_vccz .LBB0_591
	s_barrier
